# gemm_in plain tiles and gate-up epilogues: the image reads of a thread in flight together (was read, wait, store one at a time)
# speedup vs baseline: 1.0166x; 1.0034x over previous
.LBB0_58:
	s_waitcnt vmcnt(6)
	v_mul_f32_e32 v62, 0xbfb8aa3b, v92
	v_exp_f32_e32 v62, v62
	v_mov_b32_e32 v0, v163
	v_mov_b32_e32 v59, v163
	v_add_f32_e32 v62, 1.0, v62
	v_and_b32_e32 v60, 15, v0
	v_lshrrev_b32_e32 v59, 1, v59
	v_lshrrev_b32_e32 v0, 2, v0
	v_rcp_f32_e32 v62, v62
	v_lshlrev_b32_e32 v58, 6, v136
	v_and_b32_e32 v61, 32, v59
	v_and_b32_e32 v0, 12, v0
	v_or3_b32 v0, v0, v61, v58
	s_mov_b32 s2, 0xfffffc0
	v_and_or_b32 v59, v59, s2, v60
	v_lshlrev_b32_e32 v0, 1, v0
	v_lshlrev_b32_e32 v60, 7, v136
	v_sub_u32_e32 v0, v0, v60
	v_mul_f32_e32 v60, 0xbfb8aa3b, v90
	v_mul_f32_e32 v61, 0xbfb8aa3b, v91
	v_mul_f32_e32 v62, v92, v62
	v_exp_f32_e32 v60, v60
	v_exp_f32_e32 v61, v61
	v_mul_f32_e32 v63, v88, v62
	v_mul_f32_e32 v62, 0xbfb8aa3b, v93
	v_exp_f32_e32 v62, v62
	v_add_f32_e32 v60, 1.0, v60
	v_add_f32_e32 v61, 1.0, v61
	v_rcp_f32_e32 v60, v60
	v_rcp_f32_e32 v61, v61
	v_add_f32_e32 v62, 1.0, v62
	v_rcp_f32_e32 v62, v62
	v_mul_f32_e32 v60, v90, v60
	v_mul_f32_e32 v61, v91, v61
	v_mul_f32_e32 v60, v86, v60
	v_mul_f32_e32 v61, v87, v61
	v_mul_f32_e32 v62, v93, v62
	s_movk_i32 s4, 0x90
	v_mul_f32_e32 v64, v89, v62
	v_cvt_pk_bf16_f32 v62, v60, v61
	v_mad_u64_u32 v[60:61], s[2:3], v59, s4, v[0:1]
	v_mul_f32_e32 v0, 0xbfb8aa3b, v54
	v_exp_f32_e32 v0, v0
	v_cvt_pk_bf16_f32 v63, v63, v64
	v_ashrrev_i32_e32 v59, 31, v58
	v_add_f32_e32 v0, 1.0, v0
	v_rcp_f32_e32 v0, v0
	s_nop 0
	v_mul_f32_e32 v0, v54, v0
	v_mul_f32_e32 v0, v50, v0
	v_mul_f32_e32 v50, 0xbfb8aa3b, v55
	v_exp_f32_e32 v50, v50
	s_nop 0
	v_add_f32_e32 v50, 1.0, v50
	v_rcp_f32_e32 v50, v50
	s_nop 0
	v_mul_f32_e32 v50, v55, v50
	v_mul_f32_e32 v50, v51, v50
	v_cvt_pk_bf16_f32 v50, v0, v50
	v_mul_f32_e32 v0, 0xbfb8aa3b, v46
	v_exp_f32_e32 v0, v0
	v_mul_f32_e32 v51, 0xbfb8aa3b, v56
	v_exp_f32_e32 v51, v51
	v_add_f32_e32 v0, 1.0, v0
	v_rcp_f32_e32 v0, v0
	v_add_f32_e32 v51, 1.0, v51
	v_rcp_f32_e32 v51, v51
	v_mul_f32_e32 v0, v46, v0
	v_mul_f32_e32 v0, v42, v0
	v_mul_f32_e32 v42, 0xbfb8aa3b, v47
	v_exp_f32_e32 v42, v42
	v_mul_f32_e32 v51, v56, v51
	v_mul_f32_e32 v51, v52, v51
	v_mul_f32_e32 v52, 0xbfb8aa3b, v57
	v_add_f32_e32 v42, 1.0, v42
	v_rcp_f32_e32 v42, v42
	v_exp_f32_e32 v52, v52
	v_mul_f32_e32 v42, v47, v42
	v_mul_f32_e32 v42, v43, v42
	v_cvt_pk_bf16_f32 v42, v0, v42
	v_mul_f32_e32 v0, 0xbfb8aa3b, v38
	v_exp_f32_e32 v0, v0
	v_mul_f32_e32 v43, 0xbfb8aa3b, v48
	v_exp_f32_e32 v43, v43
	v_add_f32_e32 v52, 1.0, v52
	v_add_f32_e32 v0, 1.0, v0
	v_rcp_f32_e32 v0, v0
	v_add_f32_e32 v43, 1.0, v43
	v_rcp_f32_e32 v43, v43
	v_rcp_f32_e32 v52, v52
	v_mul_f32_e32 v0, v38, v0
	v_mul_f32_e32 v0, v34, v0
	v_mul_f32_e32 v34, 0xbfb8aa3b, v39
	v_exp_f32_e32 v34, v34
	v_mul_f32_e32 v43, v48, v43
	v_mul_f32_e32 v43, v44, v43
	v_mul_f32_e32 v44, 0xbfb8aa3b, v49
	v_add_f32_e32 v34, 1.0, v34
	v_rcp_f32_e32 v34, v34
	v_exp_f32_e32 v44, v44
	v_mul_f32_e32 v52, v57, v52
	v_mul_f32_e32 v52, v53, v52
	v_mul_f32_e32 v34, v39, v34
	v_mul_f32_e32 v34, v35, v34
	v_mul_f32_e32 v35, 0xbfb8aa3b, v40
	v_exp_f32_e32 v35, v35
	v_add_f32_e32 v44, 1.0, v44
	v_rcp_f32_e32 v44, v44
	v_cvt_pk_bf16_f32 v34, v0, v34
	v_add_f32_e32 v35, 1.0, v35
	v_rcp_f32_e32 v35, v35
	v_mul_f32_e32 v44, v49, v44
	v_add_u32_e32 v0, 0x800, v60
	v_mul_f32_e32 v44, v45, v44
	v_mul_f32_e32 v35, v40, v35
	v_mul_f32_e32 v35, v36, v35
	v_mul_f32_e32 v36, 0xbfb8aa3b, v41
	v_exp_f32_e32 v36, v36
	v_cvt_pk_bf16_f32 v43, v43, v44
	v_cvt_pk_bf16_f32 v51, v51, v52
	ds_write2_b64 v60, v[62:63], v[50:51] offset1:4
	v_add_f32_e32 v36, 1.0, v36
	v_rcp_f32_e32 v36, v36
	s_nop 0
	v_mul_f32_e32 v36, v41, v36
	v_mul_f32_e32 v36, v37, v36
	v_cvt_pk_bf16_f32 v35, v35, v36
	ds_write2_b64 v0, v[42:43], v[34:35] offset0:32 offset1:36
	v_mul_f32_e32 v0, 0xbfb8aa3b, v30
	v_exp_f32_e32 v0, v0
	s_nop 0
	v_add_f32_e32 v0, 1.0, v0
	v_rcp_f32_e32 v0, v0
	s_nop 0
	v_mul_f32_e32 v0, v30, v0
	v_mul_f32_e32 v0, v26, v0
	v_mul_f32_e32 v26, 0xbfb8aa3b, v31
	v_exp_f32_e32 v26, v26
	s_nop 0
	v_add_f32_e32 v26, 1.0, v26
	v_rcp_f32_e32 v26, v26
	s_nop 0
	v_mul_f32_e32 v26, v31, v26
	v_mul_f32_e32 v26, v27, v26
	v_cvt_pk_bf16_f32 v26, v0, v26
	v_mul_f32_e32 v0, 0xbfb8aa3b, v22
	v_exp_f32_e32 v0, v0
	v_mul_f32_e32 v27, 0xbfb8aa3b, v32
	v_exp_f32_e32 v27, v27
	v_add_f32_e32 v0, 1.0, v0
	v_rcp_f32_e32 v0, v0
	v_add_f32_e32 v27, 1.0, v27
	v_rcp_f32_e32 v27, v27
	v_mul_f32_e32 v0, v22, v0
	v_mul_f32_e32 v0, v18, v0
	v_mul_f32_e32 v18, 0xbfb8aa3b, v23
	v_exp_f32_e32 v18, v18
	v_mul_f32_e32 v27, v32, v27
	v_mul_f32_e32 v27, v28, v27
	v_mul_f32_e32 v28, 0xbfb8aa3b, v33
	v_add_f32_e32 v18, 1.0, v18
	v_rcp_f32_e32 v18, v18
	v_exp_f32_e32 v28, v28
	v_mul_f32_e32 v18, v23, v18
	v_mul_f32_e32 v18, v19, v18
	v_mul_f32_e32 v19, 0xbfb8aa3b, v24
	v_exp_f32_e32 v19, v19
	v_add_f32_e32 v28, 1.0, v28
	v_rcp_f32_e32 v28, v28
	v_cvt_pk_bf16_f32 v18, v0, v18
	v_add_f32_e32 v19, 1.0, v19
	v_rcp_f32_e32 v19, v19
	v_mul_f32_e32 v28, v33, v28
	v_add_u32_e32 v0, 0x1000, v60
	v_mul_f32_e32 v28, v29, v28
	v_mul_f32_e32 v19, v24, v19
	v_mul_f32_e32 v19, v20, v19
	v_mul_f32_e32 v20, 0xbfb8aa3b, v25
	v_exp_f32_e32 v20, v20
	v_cvt_pk_bf16_f32 v27, v27, v28
	s_nop 0
	v_add_f32_e32 v20, 1.0, v20
	v_rcp_f32_e32 v20, v20
	s_nop 0
	v_mul_f32_e32 v20, v25, v20
	v_mul_f32_e32 v20, v21, v20
	v_cvt_pk_bf16_f32 v19, v19, v20
	ds_write2_b64 v0, v[26:27], v[18:19] offset0:64 offset1:68
	v_mul_f32_e32 v0, 0xbfb8aa3b, v10
	v_exp_f32_e32 v0, v0
	s_nop 0
	v_add_f32_e32 v0, 1.0, v0
	v_rcp_f32_e32 v0, v0
	s_nop 0
	v_mul_f32_e32 v0, v10, v0
	v_mul_f32_e32 v10, 0xbfb8aa3b, v11
	v_exp_f32_e32 v10, v10
	v_mul_f32_e32 v0, v14, v0
	v_add_f32_e32 v10, 1.0, v10
	v_rcp_f32_e32 v10, v10
	s_nop 0
	v_mul_f32_e32 v10, v11, v10
	v_mul_f32_e32 v10, v15, v10
	v_cvt_pk_bf16_f32 v10, v0, v10
	v_mul_f32_e32 v0, 0xbfb8aa3b, v2
	v_exp_f32_e32 v0, v0
	v_mul_f32_e32 v11, 0xbfb8aa3b, v12
	v_exp_f32_e32 v11, v11
	v_add_f32_e32 v0, 1.0, v0
	v_rcp_f32_e32 v0, v0
	v_add_f32_e32 v11, 1.0, v11
	v_rcp_f32_e32 v11, v11
	v_mul_f32_e32 v0, v2, v0
	v_mul_f32_e32 v2, 0xbfb8aa3b, v3
	v_exp_f32_e32 v2, v2
	v_mul_f32_e32 v11, v12, v11
	v_mul_f32_e32 v12, 0xbfb8aa3b, v13
	v_exp_f32_e32 v12, v12
	v_add_f32_e32 v2, 1.0, v2
	v_rcp_f32_e32 v2, v2
	v_mul_f32_e32 v11, v16, v11
	v_add_f32_e32 v12, 1.0, v12
	v_rcp_f32_e32 v12, v12
	v_mul_f32_e32 v2, v3, v2
	v_mul_f32_e32 v3, 0xbfb8aa3b, v4
	v_exp_f32_e32 v3, v3
	v_mul_f32_e32 v12, v13, v12
	v_mul_f32_e32 v0, v6, v0
	v_mul_f32_e32 v2, v7, v2
	v_add_f32_e32 v3, 1.0, v3
	v_rcp_f32_e32 v3, v3
	v_mul_f32_e32 v12, v17, v12
	v_cvt_pk_bf16_f32 v11, v11, v12
	v_cvt_pk_bf16_f32 v2, v0, v2
	v_mul_f32_e32 v3, v4, v3
	v_mul_f32_e32 v4, 0xbfb8aa3b, v5
	v_exp_f32_e32 v4, v4
	v_mul_f32_e32 v3, v8, v3
	v_add_u32_e32 v0, 0x1800, v60
	v_add_f32_e32 v4, 1.0, v4
	v_rcp_f32_e32 v4, v4
	s_nop 0
	v_mul_f32_e32 v4, v5, v4
	v_mul_f32_e32 v4, v9, v4
	v_cvt_pk_bf16_f32 v3, v3, v4
	ds_write2_b64 v0, v[10:11], v[2:3] offset0:96 offset1:100
	v_mov_b32_e32 v11, v163
	s_waitcnt lgkmcnt(0)
	s_barrier
	v_lshl_add_u64 v[2:3], v[58:59], 1, s[78:79]
	v_lshlrev_b32_e32 v0, 4, v11
	v_and_b32_e32 v0, 0x70, v0
	v_ashrrev_i32_e32 v8, 3, v11
	v_lshl_add_u64 v[6:7], v[2:3], 0, v[0:1]
	v_mad_u32_u24 v12, v8, s4, v0
	ds_read_b128 v[14:17], v12
	ds_read_b128 v[18:21], v12 offset:4608
	ds_read_b128 v[22:25], v12 offset:9216
	ds_read_b128 v[26:29], v12 offset:13824
	v_lshlrev_b32_e32 v10, 7, v135
	v_add_u32_e32 v8, v8, v10
	v_mad_i64_i32 v[8:9], s[2:3], v8, s38, v[6:7]
	s_mov_b64 s[2:3], 0x2d000
	s_waitcnt lgkmcnt(3)
	global_store_dwordx4 v[8:9], v[14:17], off nt
	v_lshl_add_u64 v[8:9], v[8:9], 0, s[2:3]
	s_waitcnt lgkmcnt(2)
	global_store_dwordx4 v[8:9], v[18:21], off nt
	v_lshl_add_u64 v[8:9], v[8:9], 0, s[2:3]
	s_waitcnt lgkmcnt(1)
	global_store_dwordx4 v[8:9], v[22:25], off nt
	v_lshl_add_u64 v[8:9], v[8:9], 0, s[2:3]
	s_waitcnt lgkmcnt(0)
	global_store_dwordx4 v[8:9], v[26:29], off nt
	s_movk_i32 s2, 0x15ff
	s_barrier
	v_readlane_b32 vcc_lo, v234, 21
	s_nop 0
	v_mov_b32_e32 v0, vcc_lo
	v_add_u32_e32 v134, vcc_lo, v134
	v_cmp_lt_i32_e32 vcc, s2, v134
	s_or_b64 s[0:1], vcc, s[0:1]
	s_andn2_b64 exec, exec, s[0:1]
	s_cbranch_execz .LBB0_67

.LBB0_440:
	v_readfirstlane_b32 s12, v136
	v_readfirstlane_b32 s13, v135
	v_lshrrev_b32_e32 v5, 4, v163
	v_and_b32_e32 v6, 15, v163
	v_lshlrev_b32_e32 v6, 4, v6
	s_movk_i32 s14, 0x110
	v_mad_u32_u24 v7, v5, s14, v6
	ds_read_b128 v[210:213], v7
	ds_read_b128 v[214:217], v7 offset:4352
	ds_read_b128 v[218:221], v7 offset:8704
	ds_read_b128 v[222:225], v7 offset:13056
	ds_read_b128 v[226:229], v7 offset:17408
	ds_read_b128 v[230:233], v7 offset:21760
	ds_read_b128 v[114:117], v7 offset:26112
	ds_read_b128 v[118:121], v7 offset:30464
	s_lshl_b32 s12, s12, 7
	v_add_u32_e32 v5, s12, v5
	v_mul_u32_u24_e32 v122, 0x3300, v5
	s_lshl_b32 s13, s13, 8
	v_add3_u32 v122, v122, v6, s13
	s_andn2_b64 s[10:11], s[10:11], exec
	s_waitcnt lgkmcnt(7)
	global_store_dwordx4 v122, v[210:213], s[78:79] nt
	v_add_u32_e32 v122, 0x33000, v122
	s_waitcnt lgkmcnt(6)
	global_store_dwordx4 v122, v[214:217], s[78:79] nt
	v_add_u32_e32 v122, 0x33000, v122
	s_waitcnt lgkmcnt(5)
	global_store_dwordx4 v122, v[218:221], s[78:79] nt
	v_add_u32_e32 v122, 0x33000, v122
	s_waitcnt lgkmcnt(4)
	global_store_dwordx4 v122, v[222:225], s[78:79] nt
	v_add_u32_e32 v122, 0x33000, v122
	s_waitcnt lgkmcnt(3)
	global_store_dwordx4 v122, v[226:229], s[78:79] nt
	v_add_u32_e32 v122, 0x33000, v122
	s_waitcnt lgkmcnt(2)
	global_store_dwordx4 v122, v[230:233], s[78:79] nt
	v_add_u32_e32 v122, 0x33000, v122
	s_waitcnt lgkmcnt(1)
	global_store_dwordx4 v122, v[114:117], s[78:79] nt
	v_add_u32_e32 v122, 0x33000, v122
	s_waitcnt lgkmcnt(0)
	global_store_dwordx4 v122, v[118:121], s[78:79] nt
